# GEMM accumulator clears: pairs of v_mov_b32 replaced by v_mov_b64 (521 pairs)
# baseline (speedup 1.0000x reference)
.LBB0_94:
	s_add_u32 s24, s54, 0x100
	s_addc_u32 s25, s55, 0
	s_add_u32 s26, s52, 0x100
	v_mov_b32_e32 v2, 0
	s_addc_u32 s27, s53, 0
	s_mov_b32 s51, -2
	v_mov_b32_e32 v3, v2
	v_mov_b64_e32 v[4:5], 0
	v_mov_b64_e32 v[6:7], 0
	v_mov_b64_e32 v[8:9], 0
	v_mov_b64_e32 v[18:19], 0
	v_mov_b64_e32 v[20:21], 0
	v_mov_b64_e32 v[22:23], 0
	v_mov_b64_e32 v[24:25], 0
	v_mov_b64_e32 v[34:35], 0
	v_mov_b64_e32 v[36:37], 0
	v_mov_b64_e32 v[38:39], 0
	v_mov_b64_e32 v[40:41], 0
	v_mov_b64_e32 v[50:51], 0
	v_mov_b64_e32 v[52:53], 0
	v_mov_b64_e32 v[54:55], 0
	v_mov_b64_e32 v[56:57], 0
	v_mov_b64_e32 v[10:11], 0
	v_mov_b64_e32 v[12:13], 0
	v_mov_b64_e32 v[14:15], 0
	v_mov_b64_e32 v[16:17], 0
	v_mov_b64_e32 v[26:27], 0
	v_mov_b64_e32 v[28:29], 0
	v_mov_b64_e32 v[30:31], 0
	v_mov_b64_e32 v[32:33], 0
	v_mov_b64_e32 v[42:43], 0
	v_mov_b64_e32 v[44:45], 0
	v_mov_b64_e32 v[46:47], 0
	v_mov_b64_e32 v[48:49], 0
	v_mov_b64_e32 v[58:59], 0
	v_mov_b64_e32 v[60:61], 0
	s_waitcnt vmcnt(0)
	v_mov_b64_e32 v[62:63], 0
	v_mov_b64_e32 v[64:65], 0
	v_mov_b64_e32 v[66:67], 0
	v_mov_b64_e32 v[68:69], 0
	v_mov_b64_e32 v[70:71], 0
	v_mov_b64_e32 v[72:73], 0
	v_mov_b64_e32 v[82:83], 0
	v_mov_b64_e32 v[84:85], 0
	v_mov_b64_e32 v[86:87], 0
	v_mov_b64_e32 v[88:89], 0
	v_mov_b64_e32 v[98:99], 0
	v_mov_b64_e32 v[100:101], 0
	v_mov_b64_e32 v[102:103], 0
	v_mov_b64_e32 v[104:105], 0
	v_mov_b64_e32 v[114:115], 0
	v_mov_b64_e32 v[116:117], 0
	v_mov_b64_e32 v[118:119], 0
	v_mov_b64_e32 v[120:121], 0
	v_mov_b64_e32 v[74:75], 0
	v_mov_b64_e32 v[76:77], 0
	v_mov_b64_e32 v[78:79], 0
	v_mov_b64_e32 v[80:81], 0
	v_mov_b64_e32 v[90:91], 0
	v_mov_b64_e32 v[92:93], 0
	v_mov_b64_e32 v[94:95], 0
	v_mov_b64_e32 v[96:97], 0
	v_mov_b64_e32 v[106:107], 0
	v_mov_b64_e32 v[108:109], 0
	v_mov_b64_e32 v[110:111], 0
	v_mov_b64_e32 v[112:113], 0
	v_mov_b64_e32 v[122:123], 0
	v_mov_b64_e32 v[124:125], 0
	v_mov_b64_e32 v[126:127], 0
	v_mov_b64_e32 v[128:129], 0

.LBB0_115:
	v_readlane_b32 s40, v254, 61
	v_readlane_b32 s41, v254, 62
	s_add_u32 s70, s40, 0x16de8000
	s_addc_u32 s71, s41, 0
	s_mul_i32 s27, s35, 0x36000
	s_mul_hi_i32 s26, s35, 0x36000
	s_add_u32 s72, s40, s27
	s_addc_u32 s73, s41, s26
	s_and_b32 s26, s24, 3
	s_lshl_b32 s74, s25, 6
	v_and_b32_e32 v2, 48, v0
	s_lshl_b32 s24, s25, 13
	v_lshlrev_b32_e32 v3, 6, v0
	s_movk_i32 s25, 0x3c0
	v_lshlrev_b32_e32 v0, 2, v0
	v_and_or_b32 v2, v3, s25, v2
	v_and_b32_e32 v0, 32, v0
	v_bitop3_b32 v3, v2, s24, v0 bitop3:0xde
	s_lshl_b32 s24, s26, 12
	v_bitop3_b32 v0, v2, s24, v0 bitop3:0xde
	s_add_u32 s24, s48, 0x80
	s_addc_u32 s25, s49, 0
	s_add_i32 s75, s29, 0x18000
	s_add_i32 s80, s29, 0x1a000
	s_waitcnt vmcnt(2)
	s_barrier
	s_mov_b32 m0, s75
	s_nop 0
	global_load_lds_dwordx4 v165, s[24:25]
	s_mov_b32 m0, s80
	s_nop 0
	global_load_lds_dwordx4 v167, s[24:25]
	s_add_u32 s24, s54, 0x80
	s_addc_u32 s25, s55, 0
	s_add_i32 s81, s29, 0x8000
	s_add_i32 s82, s29, 0xa000
	s_mov_b32 m0, s81
	s_nop 0
	global_load_lds_dwordx4 v164, s[24:25]
	s_mov_b32 m0, s82
	s_nop 0
	global_load_lds_dwordx4 v166, s[24:25]
	s_add_u32 s24, s38, 0x80
	s_addc_u32 s25, s39, 0
	s_add_i32 s83, s29, 0x1c000
	s_add_i32 s84, s29, 0x1e000
	s_mov_b32 m0, s83
	s_nop 0
	global_load_lds_dwordx4 v165, s[24:25]
	s_mov_b32 m0, s84
	s_nop 0
	global_load_lds_dwordx4 v167, s[24:25]
	s_waitcnt vmcnt(6)
	s_add_i32 s85, s29, 0xc000
	s_add_i32 s86, s29, 0xe000
	s_cmpk_lt_u32 s3, 0x100
	v_readlane_b32 s3, v254, 55
	v_mov_b32_e32 v2, 0
	s_cselect_b64 s[46:47], -1, 0
	s_lshl_b32 s87, s26, 6
	s_ashr_i32 s88, s74, 31
	s_ashr_i32 s89, s3, 31
	s_mov_b32 s3, 0
	v_add_u32_e32 v168, 0, v0
	v_add_u32_e32 v169, 0, v3
	v_mov_b32_e32 v3, v2
	v_mov_b64_e32 v[4:5], 0
	v_mov_b64_e32 v[6:7], 0
	v_mov_b64_e32 v[8:9], 0
	v_mov_b64_e32 v[10:11], 0
	v_mov_b64_e32 v[12:13], 0
	v_mov_b64_e32 v[14:15], 0
	v_mov_b64_e32 v[16:17], 0
	v_mov_b64_e32 v[18:19], 0
	v_mov_b64_e32 v[20:21], 0
	v_mov_b64_e32 v[22:23], 0
	v_mov_b64_e32 v[24:25], 0
	v_mov_b64_e32 v[26:27], 0
	v_mov_b64_e32 v[28:29], 0
	v_mov_b64_e32 v[30:31], 0
	v_mov_b64_e32 v[32:33], 0
	v_mov_b64_e32 v[34:35], 0
	v_mov_b64_e32 v[36:37], 0
	v_mov_b64_e32 v[38:39], 0
	v_mov_b64_e32 v[40:41], 0
	v_mov_b64_e32 v[42:43], 0
	v_mov_b64_e32 v[44:45], 0
	v_mov_b64_e32 v[46:47], 0
	v_mov_b64_e32 v[48:49], 0
	v_mov_b64_e32 v[50:51], 0
	v_mov_b64_e32 v[52:53], 0
	v_mov_b64_e32 v[54:55], 0
	v_mov_b64_e32 v[56:57], 0
	v_mov_b64_e32 v[58:59], 0
	v_mov_b64_e32 v[60:61], 0
	s_waitcnt vmcnt(0)
	v_mov_b64_e32 v[62:63], 0
	v_mov_b64_e32 v[64:65], 0
	v_mov_b64_e32 v[66:67], 0
	v_mov_b64_e32 v[68:69], 0
	v_mov_b64_e32 v[70:71], 0
	v_mov_b64_e32 v[72:73], 0
	v_mov_b64_e32 v[74:75], 0
	v_mov_b64_e32 v[76:77], 0
	v_mov_b64_e32 v[78:79], 0
	v_mov_b64_e32 v[80:81], 0
	v_mov_b64_e32 v[82:83], 0
	v_mov_b64_e32 v[84:85], 0
	v_mov_b64_e32 v[86:87], 0
	v_mov_b64_e32 v[88:89], 0
	v_mov_b64_e32 v[90:91], 0
	v_mov_b64_e32 v[92:93], 0
	v_mov_b64_e32 v[94:95], 0
	v_mov_b64_e32 v[96:97], 0
	v_mov_b64_e32 v[98:99], 0
	v_mov_b64_e32 v[100:101], 0
	v_mov_b64_e32 v[102:103], 0
	v_mov_b64_e32 v[104:105], 0
	v_mov_b64_e32 v[106:107], 0
	v_mov_b64_e32 v[108:109], 0
	v_mov_b64_e32 v[110:111], 0
	v_mov_b64_e32 v[112:113], 0
	v_mov_b64_e32 v[114:115], 0
	v_mov_b64_e32 v[116:117], 0
	v_mov_b64_e32 v[118:119], 0
	v_mov_b64_e32 v[120:121], 0
	v_mov_b64_e32 v[122:123], 0
	v_mov_b64_e32 v[124:125], 0
	v_mov_b64_e32 v[126:127], 0
	v_mov_b64_e32 v[128:129], 0
	s_mov_b64 s[50:51], s[54:55]
	s_barrier
	s_branch .LBB0_117
.LBB0_116:
	v_mov_b32_e32 v2, 0
	v_mov_b32_e32 v3, v2
	v_mov_b64_e32 v[4:5], 0
	v_mov_b64_e32 v[6:7], 0
	v_mov_b64_e32 v[8:9], 0
	v_mov_b64_e32 v[10:11], 0
	v_mov_b64_e32 v[12:13], 0
	v_mov_b64_e32 v[14:15], 0
	v_mov_b64_e32 v[16:17], 0
	v_mov_b64_e32 v[18:19], 0
	v_mov_b64_e32 v[20:21], 0
	v_mov_b64_e32 v[22:23], 0
	v_mov_b64_e32 v[24:25], 0
	v_mov_b64_e32 v[26:27], 0
	v_mov_b64_e32 v[28:29], 0
	v_mov_b64_e32 v[30:31], 0
	v_mov_b64_e32 v[32:33], 0
	v_mov_b64_e32 v[34:35], 0
	v_mov_b64_e32 v[36:37], 0
	v_mov_b64_e32 v[38:39], 0
	v_mov_b64_e32 v[40:41], 0
	v_mov_b64_e32 v[42:43], 0
	v_mov_b64_e32 v[44:45], 0
	v_mov_b64_e32 v[46:47], 0
	v_mov_b64_e32 v[48:49], 0
	v_mov_b64_e32 v[50:51], 0
	v_mov_b64_e32 v[52:53], 0
	v_mov_b64_e32 v[54:55], 0
	v_mov_b64_e32 v[56:57], 0
	v_mov_b64_e32 v[58:59], 0
	v_mov_b64_e32 v[60:61], 0
	v_mov_b64_e32 v[62:63], 0
	v_mov_b64_e32 v[64:65], 0
	v_mov_b64_e32 v[66:67], 0
	v_mov_b64_e32 v[68:69], 0
	v_mov_b64_e32 v[70:71], 0
	v_mov_b64_e32 v[72:73], 0
	v_mov_b64_e32 v[74:75], 0
	v_mov_b64_e32 v[76:77], 0
	v_mov_b64_e32 v[78:79], 0
	v_mov_b64_e32 v[80:81], 0
	v_mov_b64_e32 v[82:83], 0
	v_mov_b64_e32 v[84:85], 0
	v_mov_b64_e32 v[86:87], 0
	v_mov_b64_e32 v[88:89], 0
	v_mov_b64_e32 v[90:91], 0
	v_mov_b64_e32 v[92:93], 0
	v_mov_b64_e32 v[94:95], 0
	v_mov_b64_e32 v[96:97], 0
	v_mov_b64_e32 v[98:99], 0
	v_mov_b64_e32 v[100:101], 0
	v_mov_b64_e32 v[102:103], 0
	v_mov_b64_e32 v[104:105], 0
	v_mov_b64_e32 v[106:107], 0
	v_mov_b64_e32 v[108:109], 0
	v_mov_b64_e32 v[110:111], 0
	v_mov_b64_e32 v[112:113], 0
	v_mov_b64_e32 v[114:115], 0
	v_mov_b64_e32 v[116:117], 0
	v_mov_b64_e32 v[118:119], 0
	v_mov_b64_e32 v[120:121], 0
	v_mov_b64_e32 v[122:123], 0
	v_mov_b64_e32 v[124:125], 0
	v_mov_b64_e32 v[126:127], 0
	v_mov_b64_e32 v[128:129], 0
	s_mov_b32 s67, s26
	s_mov_b64 s[48:49], s[42:43]
	s_mov_b32 s3, s25
	s_andn2_b64 vcc, exec, s[38:39]
	s_mov_b32 s52, s24
	s_mov_b64 s[54:55], s[50:51]
	s_cbranch_vccz .LBB0_129

.LBB0_371:
	s_add_u32 s10, s42, s4
	v_mov_b32_e32 v2, 0
	s_addc_u32 s24, s43, s5
	s_mov_b32 s25, 0
	s_mov_b64 s[40:41], -1
	s_mov_b64 s[56:57], 0
	v_mov_b32_e32 v3, v2
	v_mov_b64_e32 v[4:5], 0
	v_mov_b64_e32 v[6:7], 0
	v_mov_b64_e32 v[8:9], 0
	v_mov_b64_e32 v[18:19], 0
	v_mov_b64_e32 v[20:21], 0
	v_mov_b64_e32 v[22:23], 0
	v_mov_b64_e32 v[24:25], 0
	v_mov_b64_e32 v[34:35], 0
	v_mov_b64_e32 v[36:37], 0
	v_mov_b64_e32 v[46:47], 0
	v_mov_b64_e32 v[48:49], 0
	s_waitcnt vmcnt(0)
	v_mov_b64_e32 v[66:67], 0
	v_mov_b64_e32 v[68:69], 0
	v_mov_b64_e32 v[70:71], 0
	v_mov_b64_e32 v[72:73], 0
	v_mov_b64_e32 v[10:11], 0
	v_mov_b64_e32 v[12:13], 0
	v_mov_b64_e32 v[14:15], 0
	v_mov_b64_e32 v[16:17], 0
	v_mov_b64_e32 v[26:27], 0
	v_mov_b64_e32 v[28:29], 0
	v_mov_b64_e32 v[30:31], 0
	v_mov_b64_e32 v[32:33], 0
	v_mov_b64_e32 v[58:59], 0
	v_mov_b64_e32 v[60:61], 0
	v_mov_b64_e32 v[62:63], 0
	v_mov_b64_e32 v[64:65], 0
	v_mov_b64_e32 v[74:75], 0
	v_mov_b64_e32 v[76:77], 0
	v_mov_b64_e32 v[78:79], 0
	v_mov_b64_e32 v[80:81], 0
	v_mov_b64_e32 v[82:83], 0
	s_waitcnt vmcnt(0)
	v_mov_b64_e32 v[84:85], 0
	v_mov_b64_e32 v[86:87], 0
	v_mov_b64_e32 v[88:89], 0
	v_mov_b64_e32 v[98:99], 0
	v_mov_b64_e32 v[100:101], 0
	v_mov_b64_e32 v[102:103], 0
	v_mov_b64_e32 v[104:105], 0
	v_mov_b64_e32 v[114:115], 0
	v_mov_b64_e32 v[116:117], 0
	v_mov_b64_e32 v[118:119], 0
	v_mov_b64_e32 v[120:121], 0
	v_mov_b64_e32 v[130:131], 0
	v_mov_b64_e32 v[132:133], 0
	v_mov_b64_e32 v[134:135], 0
	v_mov_b64_e32 v[136:137], 0
	v_mov_b64_e32 v[90:91], 0
	v_mov_b64_e32 v[92:93], 0
	v_mov_b64_e32 v[94:95], 0
	v_mov_b64_e32 v[96:97], 0
	v_mov_b64_e32 v[106:107], 0
	v_mov_b64_e32 v[108:109], 0
	v_mov_b64_e32 v[110:111], 0
	v_mov_b64_e32 v[112:113], 0
	v_mov_b64_e32 v[122:123], 0
	v_mov_b64_e32 v[124:125], 0
	v_mov_b64_e32 v[126:127], 0
	v_mov_b64_e32 v[128:129], 0
	v_mov_b64_e32 v[138:139], 0
	v_mov_b64_e32 v[140:141], 0
	v_mov_b64_e32 v[142:143], 0
	v_mov_b64_e32 v[144:145], 0

.LBB0_483:
	s_add_u32 s0, s44, 0x100
	s_addc_u32 s11, s45, 0
	s_add_u32 s24, s42, 0x100
	v_mov_b32_e32 v2, 0
	s_addc_u32 s25, s43, 0
	s_mov_b32 s26, -2
	v_mov_b32_e32 v3, v2
	v_mov_b64_e32 v[4:5], 0
	v_mov_b64_e32 v[6:7], 0
	v_mov_b64_e32 v[8:9], 0
	v_mov_b64_e32 v[18:19], 0
	v_mov_b64_e32 v[20:21], 0
	v_mov_b64_e32 v[22:23], 0
	v_mov_b64_e32 v[24:25], 0
	v_mov_b64_e32 v[34:35], 0
	v_mov_b64_e32 v[36:37], 0
	v_mov_b64_e32 v[38:39], 0
	v_mov_b64_e32 v[40:41], 0
	v_mov_b64_e32 v[50:51], 0
	v_mov_b64_e32 v[52:53], 0
	v_mov_b64_e32 v[54:55], 0
	v_mov_b64_e32 v[56:57], 0
	v_mov_b64_e32 v[10:11], 0
	v_mov_b64_e32 v[12:13], 0
	v_mov_b64_e32 v[14:15], 0
	v_mov_b64_e32 v[16:17], 0
	v_mov_b64_e32 v[26:27], 0
	v_mov_b64_e32 v[28:29], 0
	v_mov_b64_e32 v[30:31], 0
	v_mov_b64_e32 v[32:33], 0
	v_mov_b64_e32 v[42:43], 0
	v_mov_b64_e32 v[44:45], 0
	v_mov_b64_e32 v[46:47], 0
	v_mov_b64_e32 v[48:49], 0
	v_mov_b64_e32 v[58:59], 0
	v_mov_b64_e32 v[60:61], 0
	v_mov_b64_e32 v[78:79], 0
	v_mov_b64_e32 v[80:81], 0
	v_mov_b64_e32 v[82:83], 0
	s_waitcnt vmcnt(0)
	v_mov_b64_e32 v[84:85], 0
	v_mov_b64_e32 v[86:87], 0
	v_mov_b64_e32 v[88:89], 0
	v_mov_b64_e32 v[98:99], 0
	v_mov_b64_e32 v[100:101], 0
	v_mov_b64_e32 v[102:103], 0
	v_mov_b64_e32 v[104:105], 0
	v_mov_b64_e32 v[114:115], 0
	v_mov_b64_e32 v[116:117], 0
	v_mov_b64_e32 v[118:119], 0
	v_mov_b64_e32 v[120:121], 0
	v_mov_b64_e32 v[130:131], 0
	v_mov_b64_e32 v[132:133], 0
	v_mov_b64_e32 v[134:135], 0
	v_mov_b64_e32 v[136:137], 0
	v_mov_b64_e32 v[90:91], 0
	v_mov_b64_e32 v[92:93], 0
	v_mov_b64_e32 v[94:95], 0
	v_mov_b64_e32 v[96:97], 0
	v_mov_b64_e32 v[106:107], 0
	v_mov_b64_e32 v[108:109], 0
	v_mov_b64_e32 v[110:111], 0
	v_mov_b64_e32 v[112:113], 0
	v_mov_b64_e32 v[122:123], 0
	v_mov_b64_e32 v[124:125], 0
	v_mov_b64_e32 v[126:127], 0
	v_mov_b64_e32 v[128:129], 0
	v_mov_b64_e32 v[138:139], 0
	v_mov_b64_e32 v[140:141], 0
	v_mov_b64_e32 v[142:143], 0
	v_mov_b64_e32 v[144:145], 0

.LBB0_607:
	s_add_u32 s11, s56, 0x100
	s_addc_u32 s45, s57, 0
	s_add_u32 s79, s54, 0x100
	v_mov_b32_e32 v2, 0
	s_addc_u32 s80, s55, 0
	s_mov_b32 s81, -2
	v_mov_b32_e32 v3, v2
	v_mov_b64_e32 v[4:5], 0
	v_mov_b64_e32 v[6:7], 0
	v_mov_b64_e32 v[8:9], 0
	v_mov_b64_e32 v[10:11], 0
	v_mov_b64_e32 v[12:13], 0
	v_mov_b64_e32 v[14:15], 0
	v_mov_b64_e32 v[16:17], 0
	v_mov_b64_e32 v[26:27], 0
	v_mov_b64_e32 v[28:29], 0
	v_mov_b64_e32 v[30:31], 0
	v_mov_b64_e32 v[32:33], 0
	v_mov_b64_e32 v[42:43], 0
	v_mov_b64_e32 v[44:45], 0
	v_mov_b64_e32 v[46:47], 0
	v_mov_b64_e32 v[48:49], 0
	v_mov_b64_e32 v[18:19], 0
	v_mov_b64_e32 v[20:21], 0
	v_mov_b64_e32 v[22:23], 0
	v_mov_b64_e32 v[24:25], 0
	v_mov_b64_e32 v[34:35], 0
	v_mov_b64_e32 v[36:37], 0
	v_mov_b64_e32 v[38:39], 0
	v_mov_b64_e32 v[40:41], 0
	v_mov_b64_e32 v[50:51], 0
	v_mov_b64_e32 v[52:53], 0
	v_mov_b64_e32 v[54:55], 0
	v_mov_b64_e32 v[56:57], 0
	v_mov_b64_e32 v[58:59], 0
	v_mov_b64_e32 v[60:61], 0
	v_mov_b64_e32 v[62:63], 0
	v_mov_b64_e32 v[64:65], 0
	v_mov_b64_e32 v[66:67], 0
	v_mov_b64_e32 v[68:69], 0
	v_mov_b64_e32 v[70:71], 0
	v_mov_b64_e32 v[72:73], 0
	v_mov_b64_e32 v[74:75], 0
	v_mov_b64_e32 v[76:77], 0
	v_mov_b64_e32 v[78:79], 0
	v_mov_b64_e32 v[80:81], 0
	v_mov_b64_e32 v[86:87], 0
	v_mov_b64_e32 v[88:89], 0
	v_mov_b64_e32 v[94:95], 0
	v_mov_b64_e32 v[96:97], 0
	v_mov_b64_e32 v[102:103], 0
	v_mov_b64_e32 v[104:105], 0
	v_mov_b64_e32 v[110:111], 0
	v_mov_b64_e32 v[112:113], 0
	v_mov_b64_e32 v[82:83], 0
	v_mov_b64_e32 v[84:85], 0
	v_mov_b64_e32 v[90:91], 0
	v_mov_b64_e32 v[92:93], 0
	v_mov_b64_e32 v[98:99], 0
	v_mov_b64_e32 v[100:101], 0
	v_mov_b64_e32 v[106:107], 0
	v_mov_b64_e32 v[108:109], 0
	v_mov_b64_e32 v[114:115], 0
	v_mov_b64_e32 v[116:117], 0
	v_mov_b64_e32 v[118:119], 0
	v_mov_b64_e32 v[120:121], 0
	v_mov_b64_e32 v[122:123], 0
	v_mov_b64_e32 v[124:125], 0
	v_mov_b64_e32 v[126:127], 0
	v_mov_b64_e32 v[128:129], 0

.LBB0_638:
	s_add_u32 s46, s52, 0x16de8000
	s_addc_u32 s47, s53, 0
	s_sub_i32 s25, s85, 28
	v_readlane_b32 s40, v254, 51
	s_cmp_lt_u32 s25, 9
	v_readlane_b32 s41, v254, 52
	s_mul_i32 s26, s35, 0x36000
	s_cselect_b32 s49, s41, 0
	s_cselect_b32 s48, s40, 0
	s_mul_hi_i32 s25, s35, 0x36000
	s_add_u32 s80, s52, s26
	s_addc_u32 s81, s53, s25
	v_and_b32_e32 v2, 48, v0
	v_lshlrev_b32_e32 v3, 6, v0
	s_movk_i32 s25, 0x3c0
	v_lshlrev_b32_e32 v0, 2, v0
	s_and_b32 s11, s11, 3
	s_lshl_b32 s82, s24, 6
	s_lshl_b32 s24, s24, 13
	v_and_or_b32 v2, v3, s25, v2
	v_and_b32_e32 v0, 32, v0
	v_bitop3_b32 v3, v2, s24, v0 bitop3:0xde
	s_lshl_b32 s24, s11, 12
	v_bitop3_b32 v0, v2, s24, v0 bitop3:0xde
	s_add_u32 s24, s54, 0x80
	s_addc_u32 s25, s55, 0
	s_add_i32 s83, s31, 0x18000
	s_add_i32 s84, s31, 0x1a000
	s_waitcnt vmcnt(2)
	s_barrier
	s_mov_b32 m0, s83
	s_nop 0
	global_load_lds_dwordx4 v216, s[24:25]
	s_mov_b32 m0, s84
	s_nop 0
	global_load_lds_dwordx4 v218, s[24:25]
	s_add_u32 s24, s62, 0x80
	s_mov_b32 s2, s85
	s_addc_u32 s25, s63, 0
	s_add_i32 s85, s31, 0x8000
	s_add_i32 s86, s31, 0xa000
	s_mov_b32 m0, s85
	s_nop 0
	global_load_lds_dwordx4 v215, s[24:25]
	s_mov_b32 m0, s86
	s_nop 0
	global_load_lds_dwordx4 v217, s[24:25]
	s_add_u32 s24, s38, 0x80
	s_addc_u32 s25, s39, 0
	s_add_i32 s87, s31, 0x1c000
	s_add_i32 s88, s31, 0x1e000
	s_add_i32 s89, s31, 0xc000
	s_add_i32 s90, s31, 0xe000
	s_mov_b32 m0, s87
	s_nop 0
	global_load_lds_dwordx4 v216, s[24:25]
	s_mov_b32 m0, s88
	s_nop 0
	global_load_lds_dwordx4 v218, s[24:25]
	s_cmpk_lt_u32 s10, 0x100
	v_readlane_b32 s10, v254, 55
	s_waitcnt vmcnt(6)
	s_cselect_b64 s[50:51], -1, 0
	s_lshl_b32 s91, s11, 6
	s_ashr_i32 s97, s82, 31
	s_ashr_i32 s92, s10, 31
	v_mov_b32_e32 v2, 0
	s_cmp_lg_u64 s[48:49], 0
	s_mov_b32 s93, 0
	s_cselect_b64 s[52:53], -1, 0
	v_add_u32_e32 v219, 0, v0
	v_add_u32_e32 v220, 0, v3
	v_mov_b32_e32 v3, v2
	v_mov_b64_e32 v[4:5], 0
	v_mov_b64_e32 v[6:7], 0
	v_mov_b64_e32 v[8:9], 0
	v_mov_b64_e32 v[10:11], 0
	v_mov_b64_e32 v[12:13], 0
	v_mov_b64_e32 v[14:15], 0
	v_mov_b64_e32 v[16:17], 0
	v_mov_b64_e32 v[18:19], 0
	v_mov_b64_e32 v[20:21], 0
	v_mov_b64_e32 v[22:23], 0
	v_mov_b64_e32 v[24:25], 0
	v_mov_b64_e32 v[26:27], 0
	v_mov_b64_e32 v[28:29], 0
	v_mov_b64_e32 v[30:31], 0
	v_mov_b64_e32 v[32:33], 0
	v_mov_b64_e32 v[34:35], 0
	v_mov_b64_e32 v[36:37], 0
	v_mov_b64_e32 v[38:39], 0
	v_mov_b64_e32 v[40:41], 0
	v_mov_b64_e32 v[42:43], 0
	v_mov_b64_e32 v[44:45], 0
	v_mov_b64_e32 v[46:47], 0
	v_mov_b64_e32 v[48:49], 0
	v_mov_b64_e32 v[50:51], 0
	v_mov_b64_e32 v[52:53], 0
	v_mov_b64_e32 v[54:55], 0
	v_mov_b64_e32 v[56:57], 0
	v_mov_b64_e32 v[58:59], 0
	v_mov_b64_e32 v[60:61], 0
	s_waitcnt vmcnt(0)
	v_mov_b64_e32 v[62:63], 0
	v_mov_b64_e32 v[64:65], 0
	v_mov_b64_e32 v[66:67], 0
	v_mov_b64_e32 v[68:69], 0
	v_mov_b64_e32 v[70:71], 0
	v_mov_b64_e32 v[72:73], 0
	v_mov_b64_e32 v[74:75], 0
	v_mov_b64_e32 v[76:77], 0
	v_mov_b64_e32 v[78:79], 0
	v_mov_b64_e32 v[80:81], 0
	v_mov_b64_e32 v[82:83], 0
	v_mov_b64_e32 v[84:85], 0
	v_mov_b64_e32 v[86:87], 0
	v_mov_b64_e32 v[88:89], 0
	v_mov_b64_e32 v[90:91], 0
	v_mov_b64_e32 v[92:93], 0
	v_mov_b64_e32 v[94:95], 0
	v_mov_b64_e32 v[96:97], 0
	v_mov_b64_e32 v[98:99], 0
	v_mov_b64_e32 v[100:101], 0
	v_mov_b64_e32 v[102:103], 0
	v_mov_b64_e32 v[104:105], 0
	v_mov_b64_e32 v[106:107], 0
	v_mov_b64_e32 v[108:109], 0
	v_mov_b64_e32 v[110:111], 0
	v_mov_b64_e32 v[112:113], 0
	v_mov_b64_e32 v[114:115], 0
	v_mov_b64_e32 v[116:117], 0
	v_mov_b64_e32 v[118:119], 0
	v_mov_b64_e32 v[120:121], 0
	v_mov_b64_e32 v[122:123], 0
	v_mov_b64_e32 v[124:125], 0
	v_mov_b64_e32 v[126:127], 0
	v_mov_b64_e32 v[128:129], 0
	s_mov_b64 s[56:57], s[62:63]
	v_readlane_b32 s42, v254, 53
	v_readlane_b32 s43, v254, 54
	s_barrier
	s_branch .LBB0_640
.LBB0_639:
	v_mov_b32_e32 v2, 0
	v_mov_b32_e32 v3, v2
	v_mov_b64_e32 v[4:5], 0
	v_mov_b64_e32 v[6:7], 0
	v_mov_b64_e32 v[8:9], 0
	v_mov_b64_e32 v[10:11], 0
	v_mov_b64_e32 v[12:13], 0
	v_mov_b64_e32 v[14:15], 0
	v_mov_b64_e32 v[16:17], 0
	v_mov_b64_e32 v[18:19], 0
	v_mov_b64_e32 v[20:21], 0
	v_mov_b64_e32 v[22:23], 0
	v_mov_b64_e32 v[24:25], 0
	v_mov_b64_e32 v[26:27], 0
	v_mov_b64_e32 v[28:29], 0
	v_mov_b64_e32 v[30:31], 0
	v_mov_b64_e32 v[32:33], 0
	v_mov_b64_e32 v[34:35], 0
	v_mov_b64_e32 v[36:37], 0
	v_mov_b64_e32 v[38:39], 0
	v_mov_b64_e32 v[40:41], 0
	v_mov_b64_e32 v[42:43], 0
	v_mov_b64_e32 v[44:45], 0
	v_mov_b64_e32 v[46:47], 0
	v_mov_b64_e32 v[48:49], 0
	v_mov_b64_e32 v[50:51], 0
	v_mov_b64_e32 v[52:53], 0
	v_mov_b64_e32 v[54:55], 0
	v_mov_b64_e32 v[56:57], 0
	v_mov_b64_e32 v[58:59], 0
	v_mov_b64_e32 v[60:61], 0
	v_mov_b64_e32 v[62:63], 0
	v_mov_b64_e32 v[64:65], 0
	v_mov_b64_e32 v[66:67], 0
	v_mov_b64_e32 v[68:69], 0
	v_mov_b64_e32 v[70:71], 0
	v_mov_b64_e32 v[72:73], 0
	v_mov_b64_e32 v[74:75], 0
	v_mov_b64_e32 v[76:77], 0
	v_mov_b64_e32 v[78:79], 0
	v_mov_b64_e32 v[80:81], 0
	v_mov_b64_e32 v[82:83], 0
	v_mov_b64_e32 v[84:85], 0
	v_mov_b64_e32 v[86:87], 0
	v_mov_b64_e32 v[88:89], 0
	v_mov_b64_e32 v[90:91], 0
	v_mov_b64_e32 v[92:93], 0
	v_mov_b64_e32 v[94:95], 0
	v_mov_b64_e32 v[96:97], 0
	v_mov_b64_e32 v[98:99], 0
	v_mov_b64_e32 v[100:101], 0
	v_mov_b64_e32 v[102:103], 0
	v_mov_b64_e32 v[104:105], 0
	v_mov_b64_e32 v[106:107], 0
	v_mov_b64_e32 v[108:109], 0
	v_mov_b64_e32 v[110:111], 0
	v_mov_b64_e32 v[112:113], 0
	v_mov_b64_e32 v[114:115], 0
	v_mov_b64_e32 v[116:117], 0
	v_mov_b64_e32 v[118:119], 0
	v_mov_b64_e32 v[120:121], 0
	v_mov_b64_e32 v[122:123], 0
	v_mov_b64_e32 v[124:125], 0
	v_mov_b64_e32 v[126:127], 0
	v_mov_b64_e32 v[128:129], 0
	s_mov_b32 s3, s78
	s_mov_b64 s[54:55], s[60:61]
	s_mov_b32 s93, s95
	s_andn2_b64 vcc, exec, s[38:39]
	s_mov_b32 s58, s94
	s_mov_b64 s[62:63], s[56:57]
	s_cbranch_vccz .LBB0_716

.LBB0_1532:
	s_or_b64 exec, exec, s[4:5]
	s_mul_hi_i32 s3, s0, 0x2aaaaaab
	s_lshr_b32 s4, s3, 31
	s_ashr_i32 s3, s3, 3
	s_add_i32 s3, s3, s4
	s_mul_i32 s4, s3, 48
	v_ashrrev_i32_e32 v0, 5, v78
	s_sub_i32 s10, s0, s4
	v_lshlrev_b32_e32 v2, 6, v0
	s_lshl_b32 s4, s10, 7
	v_mad_i64_i32 v[2:3], s[6:7], v2, s9, 0
	s_ashr_i32 s5, s4, 31
	v_mad_i64_i32 v[2:3], s[6:7], s3, v238, v[2:3]
	s_lshl_b64 s[6:7], s[4:5], 2
	v_readlane_b32 s20, v253, 58
	v_and_b32_e32 v4, 31, v78
	v_readlane_b32 s21, v253, 59
	s_add_u32 s6, s20, s6
	v_lshl_or_b32 v2, v4, 4, v2
	s_addc_u32 s7, s21, s7
	s_waitcnt vmcnt(0)
	v_lshl_add_u64 v[74:75], s[6:7], 0, v[2:3]
	v_mov_b32_e32 v2, 0
	v_lshl_add_u32 v80, v0, 8, 0
	s_mov_b64 s[6:7], 0
	v_mov_b32_e32 v3, v2
	v_mov_b64_e32 v[4:5], 0
	v_mov_b64_e32 v[6:7], 0
	v_mov_b64_e32 v[8:9], 0
	v_mov_b64_e32 v[10:11], 0
	v_mov_b64_e32 v[12:13], 0
	v_mov_b64_e32 v[14:15], 0
	v_mov_b64_e32 v[16:17], 0
	v_mov_b64_e32 v[18:19], 0
	v_mov_b64_e32 v[20:21], 0
	v_mov_b64_e32 v[22:23], 0
	v_mov_b64_e32 v[24:25], 0
	v_mov_b64_e32 v[26:27], 0
	v_mov_b64_e32 v[28:29], 0
	v_mov_b64_e32 v[30:31], 0
	v_mov_b64_e32 v[32:33], 0
	v_mov_b64_e32 v[34:35], 0
	v_mov_b64_e32 v[36:37], 0
	s_waitcnt lgkmcnt(0)
	s_barrier
	v_readlane_b32 s22, v253, 60
	v_readlane_b32 s23, v253, 61
